# attention BR2: K/V fragment reads issued early, next step chunk-list pair prefetched before the step barrier
# speedup vs baseline: 1.0081x; 1.0039x over previous
.LBB0_619:
	s_or_b64 exec, exec, s[0:1]
	v_lshlrev_b32_e32 v29, 5, v111
	v_add_u32_e32 v0, s68, v29
	v_or_b32_e32 v160, v0, v109
	v_or_b32_e32 v156, 16, v160
	v_ashrrev_i32_e32 v161, 31, v160
	v_ashrrev_i32_e32 v157, 31, v156
	v_lshlrev_b64 v[164:165], 12, v[160:161]
	v_lshlrev_b64 v[162:163], 12, v[156:157]
	v_lshl_add_u64 v[12:13], v[82:83], 0, v[164:165]
	v_lshl_add_u64 v[30:31], v[82:83], 0, v[162:163]
	s_waitcnt lgkmcnt(0)
	s_barrier
	flat_load_dwordx4 v[0:3], v[12:13]
	flat_load_dwordx4 v[4:7], v[12:13] offset:64
	flat_load_dwordx4 v[8:11], v[12:13] offset:128
	s_nop 0
	flat_load_dwordx4 v[12:15], v[12:13] offset:192
	s_nop 0
	flat_load_dwordx4 v[16:19], v[30:31]
	flat_load_dwordx4 v[20:23], v[30:31] offset:64
	flat_load_dwordx4 v[24:27], v[30:31] offset:128
	flat_load_dwordx4 v[32:35], v[30:31] offset:192
	v_readlane_b32 s0, v246, 6
	s_lshl_b32 s26, s69, 7
	s_lshl_b32 s27, s69, 20
	v_mov_b32_e32 v30, s0
	ds_read_b32 v30, v30
	s_waitcnt lgkmcnt(0)
	v_cmp_eq_u32_e32 vcc, 0, v30
	v_readfirstlane_b32 s28, v30
	s_cbranch_vccnz .LBB0_679
	v_mov_b32_e32 v52, v154
	v_mov_b32_e32 v30, v155
	v_mov_b32_e32 v31, s50
	ds_read_b32 v31, v31
	s_lshl_b32 s0, s26, 1
	s_add_u32 s12, s43, s0
	s_addc_u32 s13, s42, 0
	s_lshl_b32 s0, s27, 1
	s_add_u32 s14, s45, s0
	s_mov_b32 s0, 0x60000
	s_waitcnt lgkmcnt(0)
	v_mul_hi_i32 v37, v31, s0
	v_mul_lo_u32 v36, v31, s0
	v_lshl_add_u64 v[40:41], s[12:13], 0, v[36:37]
	v_lshlrev_b32_e32 v36, 6, v31
	v_ashrrev_i32_e32 v37, 31, v36
	s_addc_u32 s15, s44, 0
	v_lshlrev_b64 v[36:37], 1, v[36:37]
	v_lshlrev_b32_e32 v31, 3, v52
	v_lshrrev_b32_e32 v53, 4, v52
	s_movk_i32 s0, 0xc00
	v_lshl_add_u64 v[48:49], s[14:15], 0, v[36:37]
	v_and_b32_e32 v42, 0x78, v31
	v_mul_lo_u32 v36, v53, s0
	v_or_b32_e32 v166, v36, v42
	v_mov_b32_e32 v167, v28
	v_lshl_add_u64 v[36:37], v[166:167], 1, v[40:41]
	v_add_u32_e32 v54, 0x200, v52
	global_load_dwordx4 v[36:39], v[36:37], off offset:2048
	v_lshrrev_b32_e32 v55, 4, v54
	v_mul_lo_u32 v43, v55, s0
	v_and_b32_e32 v31, 56, v31
	v_lshlrev_b32_e32 v44, 10, v52
	s_movk_i32 s0, 0xe000
	v_lshlrev_b32_e32 v50, 10, v54
	v_or_b32_e32 v168, v43, v42
	v_mov_b32_e32 v169, v28
	v_and_or_b32 v170, v44, s0, v31
	v_mov_b32_e32 v171, v28
	v_and_or_b32 v172, v50, s0, v31
	v_mov_b32_e32 v173, v28
	v_lshl_add_u64 v[40:41], v[168:169], 1, v[40:41]
	v_lshl_add_u64 v[44:45], v[170:171], 1, v[48:49]
	v_lshl_add_u64 v[48:49], v[172:173], 1, v[48:49]
	global_load_dwordx4 v[40:43], v[40:41], off offset:2048
	v_lshlrev_b32_e32 v56, 4, v52
	global_load_dwordx4 v[44:47], v[44:45], off
	v_and_b32_e32 v31, 0xf0, v56
	global_load_dwordx4 v[48:51], v[48:49], off
	v_add_u32_e32 v57, s54, v31
	v_mul_lo_u32 v157, v53, s83
	v_add_u32_e32 v161, v57, v157
	v_mul_lo_u32 v189, v55, s83
	v_add_u32_e32 v190, v57, v189
	v_readfirstlane_b32 s0, v160
	s_cmp_lt_i32 s28, 1
	s_waitcnt vmcnt(0)
	ds_write_b128 v161, v[36:39]
	v_lshrrev_b32_e32 v38, 3, v52
	v_and_b32_e32 v36, 0x70, v56
	v_mul_lo_u32 v191, v38, s88
	v_lshrrev_b32_e32 v38, 3, v54
	v_add_u32_e32 v37, s79, v36
	v_mul_lo_u32 v193, v38, s88
	v_add_u32_e32 v192, v37, v191
	v_add_u32_e32 v194, v37, v193
	ds_write_b128 v190, v[40:43]
	ds_write_b128 v192, v[44:47]
	ds_write_b128 v194, v[48:51]
	s_waitcnt lgkmcnt(0)
	s_barrier
	s_cbranch_scc1 .LBB0_680
	v_or_b32_e32 v29, v29, v109
	s_add_i32 s1, 0, 0x14440
	v_lshl_add_u32 v195, v29, 4, s1
	v_and_b32_e32 v29, 15, v30
	v_and_b32_e32 v37, -16, v30
	v_ashrrev_i32_e32 v30, 4, v30
	v_lshlrev_b32_e32 v209, 2, v30
	v_lshlrev_b32_e32 v30, 3, v30
	v_add_u32_e32 v38, s54, v37
	v_mul_u32_u24_e32 v39, 0x110, v29
	v_add_u32_e32 v40, s79, v30
	v_mul_u32_u24_e32 v41, 0x90, v29
	v_add_u32_e32 v210, 0, v36
	v_add_u32_e32 v211, 0, v31
	v_add_u32_e32 v36, 0, v37
	v_add_u32_e32 v37, 0, v30
	v_mov_b32_e32 v30, v28
	v_mov_b32_e32 v31, v28
	v_mov_b32_e32 v29, v28
	v_add_u32_e32 v212, v38, v39
	v_add_u32_e32 v213, v40, v41
	v_add_u32_e32 v214, v36, v39
	v_add_u32_e32 v215, v37, v41
	v_mov_b64_e32 v[38:39], v[30:31]
	v_mov_b64_e32 v[42:43], v[30:31]
	v_mov_b64_e32 v[46:47], v[30:31]
	v_mov_b64_e32 v[50:51], v[30:31]
	v_mov_b64_e32 v[54:55], v[30:31]
	v_mov_b64_e32 v[58:59], v[30:31]
	v_mov_b64_e32 v[62:63], v[30:31]
	v_mov_b64_e32 v[66:67], v[30:31]
	v_mov_b64_e32 v[70:71], v[30:31]
	v_mov_b64_e32 v[74:75], v[30:31]
	v_mov_b64_e32 v[78:79], v[30:31]
	v_mov_b64_e32 v[82:83], v[30:31]
	v_mov_b64_e32 v[86:87], v[30:31]
	v_mov_b64_e32 v[90:91], v[30:31]
	v_mov_b64_e32 v[94:95], v[30:31]
	v_mov_b64_e32 v[98:99], v[30:31]
	s_sub_i32 s29, s0, 63
	s_mov_b32 s31, 0
	v_mov_b32_e32 v217, 0xf149f2ca
	v_mov_b32_e32 v117, 0
	v_readlane_b32 s30, v244, 7
	v_mov_b64_e32 v[36:37], v[28:29]
	v_mov_b64_e32 v[40:41], v[28:29]
	v_mov_b64_e32 v[44:45], v[28:29]
	v_mov_b64_e32 v[48:49], v[28:29]
	v_mov_b64_e32 v[52:53], v[28:29]
	v_mov_b64_e32 v[56:57], v[28:29]
	v_mov_b64_e32 v[60:61], v[28:29]
	v_mov_b64_e32 v[64:65], v[28:29]
	v_mov_b64_e32 v[68:69], v[28:29]
	v_mov_b64_e32 v[72:73], v[28:29]
	v_mov_b64_e32 v[76:77], v[28:29]
	v_mov_b64_e32 v[80:81], v[28:29]
	v_mov_b64_e32 v[84:85], v[28:29]
	v_mov_b64_e32 v[88:89], v[28:29]
	v_mov_b64_e32 v[92:93], v[28:29]
	v_mov_b64_e32 v[96:97], v[28:29]
	v_mov_b32_e32 v116, 0
	v_mov_b32_e32 v218, 0xf149f2ca
	v_mov_b32_e32 v216, 0
	v_mov_b32_e32 v29, 0
	ds_read_b32 v239, v151 offset:9728
	s_waitcnt lgkmcnt(0)
	v_readfirstlane_b32 s32, v239
	s_add_i32 s98, s30, -8
	v_mov_b32_e32 v239, s98
	ds_read_b32 v247, v239 offset:4
	ds_read_b32 v239, v239
	s_waitcnt lgkmcnt(0)
	s_branch .LBB0_623

.LBB0_623:
	ds_read_b128 v[174:177], v212
	ds_read_b128 v[240:243], v212 offset:64
	ds_read_b128 v[248:251], v212 offset:128
	ds_read_b128 v[252:255], v212 offset:192
	s_add_i32 s0, s31, 1
	s_cmp_lt_i32 s0, s28
	s_cselect_b64 s[18:19], -1, 0
	s_cmp_ge_i32 s0, s28
	s_cselect_b64 s[16:17], -1, 0
	v_readfirstlane_b32 s2, v239
	v_readfirstlane_b32 s3, v247
	s_ashr_i32 s98, s2, 5
	v_lshl_add_u32 v239, s98, 2, v195
	ds_read_b32 v247, v239 offset:256
	ds_read_b32 v239, v239
	s_and_b64 vcc, exec, s[16:17]
	s_waitcnt vmcnt(0)
	v_mov_b32_e32 v100, 0
	v_mov_b32_e32 v101, 0
	v_mov_b32_e32 v102, 0
	v_mov_b32_e32 v103, 0
	v_mov_b32_e32 v104, 0
	v_mov_b32_e32 v105, 0
	v_mov_b32_e32 v106, 0
	v_mov_b32_e32 v107, 0
	v_mov_b32_e32 v108, 0
	v_mov_b32_e32 v109, 0
	v_mov_b32_e32 v110, 0
	v_mov_b32_e32 v111, 0
	v_mov_b32_e32 v112, 0
	v_mov_b32_e32 v113, 0
	v_mov_b32_e32 v114, 0
	v_mov_b32_e32 v115, 0
	s_cbranch_vccnz .LBB0_625
	s_mul_i32 s0, s3, 0x60000
	s_mul_hi_i32 s1, s3, 0x60000
	s_add_u32 s0, s12, s0
	s_addc_u32 s1, s13, s1
	s_lshl_b32 s8, s3, 6
	s_ashr_i32 s9, s8, 31
	v_lshl_add_u64 v[30:31], v[166:167], 1, s[0:1]
	v_lshl_add_u64 v[100:101], v[168:169], 1, s[0:1]
	s_lshl_b64 s[0:1], s[8:9], 1
	s_add_u32 s0, s14, s0
	s_addc_u32 s1, s15, s1
	global_load_dwordx4 v[104:107], v[30:31], off offset:2048
	global_load_dwordx4 v[108:111], v[100:101], off offset:2048
	v_lshl_add_u64 v[30:31], v[170:171], 1, s[0:1]
	v_lshl_add_u64 v[100:101], v[172:173], 1, s[0:1]
	global_load_dwordx4 v[112:115], v[30:31], off
	s_nop 0
	global_load_dwordx4 v[100:103], v[100:101], off
.LBB0_625:
	s_lshl_b32 s0, 1, s2
	s_waitcnt lgkmcnt(0)
	v_and_b32_e32 v31, s0, v247
	v_and_b32_e32 v30, s0, v239
	v_or_b32_e32 v118, v30, v31
	v_cmp_ne_u32_e64 s[8:9], 0, v31
	v_cmp_ne_u32_e64 s[0:1], 0, v30
	v_cmp_ne_u32_e32 vcc, 0, v118
	s_cbranch_vccz .LBB0_677
	s_lshl_b32 s2, s2, 6
	v_cndmask_b32_e64 v30, 0, 1, s[8:9]
	v_cndmask_b32_e64 v31, 0, 1, s[0:1]
	s_sub_i32 s0, s29, s2
	v_lshlrev_b16_e32 v30, 8, v30
	s_cmpk_lt_i32 s0, 0x80
	v_or_b32_e32 v30, v31, v30
	s_cselect_b64 s[20:21], -1, 0
	s_cmpk_gt_i32 s0, 0x7f
	s_setprio 1
	s_waitcnt lgkmcnt(3)
	v_mfma_f32_16x16x32_bf16 v[132:135], v[174:177], v[0:3], 0
	v_mfma_f32_16x16x32_bf16 v[116:119], v[174:177], v[16:19], 0
	ds_read_b128 v[174:177], v212 offset:4352
	s_waitcnt lgkmcnt(3)
	v_mfma_f32_16x16x32_bf16 v[132:135], v[240:243], v[4:7], v[132:135]
	v_mfma_f32_16x16x32_bf16 v[116:119], v[240:243], v[20:23], v[116:119]
	ds_read_b128 v[240:243], v212 offset:4416
	s_waitcnt lgkmcnt(3)
	v_mfma_f32_16x16x32_bf16 v[132:135], v[248:251], v[8:11], v[132:135]
	v_mfma_f32_16x16x32_bf16 v[116:119], v[248:251], v[24:27], v[116:119]
	ds_read_b128 v[248:251], v212 offset:4480
	s_waitcnt lgkmcnt(3)
	v_mfma_f32_16x16x32_bf16 v[132:135], v[252:255], v[12:15], v[132:135]
	v_mfma_f32_16x16x32_bf16 v[116:119], v[252:255], v[32:35], v[116:119]
	ds_read_b128 v[252:255], v212 offset:4544
	s_waitcnt lgkmcnt(3)
	v_mfma_f32_16x16x32_bf16 v[136:139], v[174:177], v[0:3], 0
	v_mfma_f32_16x16x32_bf16 v[120:123], v[174:177], v[16:19], 0
	ds_read_b128 v[174:177], v212 offset:8704
	s_waitcnt lgkmcnt(3)
	v_mfma_f32_16x16x32_bf16 v[136:139], v[240:243], v[4:7], v[136:139]
	v_mfma_f32_16x16x32_bf16 v[120:123], v[240:243], v[20:23], v[120:123]
	ds_read_b128 v[240:243], v212 offset:8768
	s_waitcnt lgkmcnt(3)
	v_mfma_f32_16x16x32_bf16 v[136:139], v[248:251], v[8:11], v[136:139]
	v_mfma_f32_16x16x32_bf16 v[120:123], v[248:251], v[24:27], v[120:123]
	ds_read_b128 v[248:251], v212 offset:8832
	s_waitcnt lgkmcnt(3)
	v_mfma_f32_16x16x32_bf16 v[136:139], v[252:255], v[12:15], v[136:139]
	v_mfma_f32_16x16x32_bf16 v[120:123], v[252:255], v[32:35], v[120:123]
	ds_read_b128 v[252:255], v212 offset:8896
	s_waitcnt lgkmcnt(3)
	v_mfma_f32_16x16x32_bf16 v[140:143], v[174:177], v[0:3], 0
	v_mfma_f32_16x16x32_bf16 v[124:127], v[174:177], v[16:19], 0
	ds_read_b128 v[174:177], v212 offset:13056
	s_waitcnt lgkmcnt(3)
	v_mfma_f32_16x16x32_bf16 v[140:143], v[240:243], v[4:7], v[140:143]
	v_mfma_f32_16x16x32_bf16 v[124:127], v[240:243], v[20:23], v[124:127]
	ds_read_b128 v[240:243], v212 offset:13120
	s_waitcnt lgkmcnt(3)
	v_mfma_f32_16x16x32_bf16 v[140:143], v[248:251], v[8:11], v[140:143]
	v_mfma_f32_16x16x32_bf16 v[124:127], v[248:251], v[24:27], v[124:127]
	ds_read_b128 v[248:251], v212 offset:13184
	s_waitcnt lgkmcnt(3)
	v_mfma_f32_16x16x32_bf16 v[140:143], v[252:255], v[12:15], v[140:143]
	v_mfma_f32_16x16x32_bf16 v[124:127], v[252:255], v[32:35], v[124:127]
	ds_read_b128 v[252:255], v212 offset:13248
	s_waitcnt lgkmcnt(3)
	v_mfma_f32_16x16x32_bf16 v[144:147], v[174:177], v[0:3], 0
	v_mfma_f32_16x16x32_bf16 v[128:131], v[174:177], v[16:19], 0
	s_waitcnt lgkmcnt(2)
	v_mfma_f32_16x16x32_bf16 v[144:147], v[240:243], v[4:7], v[144:147]
	v_mfma_f32_16x16x32_bf16 v[128:131], v[240:243], v[20:23], v[128:131]
	s_waitcnt lgkmcnt(1)
	v_mfma_f32_16x16x32_bf16 v[144:147], v[248:251], v[8:11], v[144:147]
	v_mfma_f32_16x16x32_bf16 v[128:131], v[248:251], v[24:27], v[128:131]
	s_waitcnt lgkmcnt(0)
	v_mfma_f32_16x16x32_bf16 v[144:147], v[252:255], v[12:15], v[144:147]
	v_mfma_f32_16x16x32_bf16 v[128:131], v[252:255], v[32:35], v[128:131]
	s_setprio 0
	ds_read2_b64 v[240:243], v213 offset1:4
	v_add_u32_e32 v239, 0x800, v213
	ds_read2_b64 v[248:251], v239 offset0:32 offset1:36
	v_add_u32_e32 v247, 0x1000, v213
	ds_read2_b64 v[252:255], v247 offset0:64 offset1:68
	v_add_u32_e32 v237, s2, v209
	s_mov_b64 s[0:1], -1
	v_and_b32_e32 v238, 1, v30
	v_or_b32_e32 v236, 2, v237
	v_or_b32_e32 v220, 3, v237
	s_cbranch_scc1 .LBB0_628
	v_sub_u32_e32 v179, v160, v237
	v_med3_i32 v30, v179, 0, v207
	v_lshl_add_u32 v30, v30, 2, v151
	ds_read_b32 v30, v30 offset:9216
	v_cmp_lt_i32_e64 s[0:1], -1, v179
	v_cmp_eq_u32_e32 vcc, 1, v238
	s_and_b64 s[0:1], s[0:1], vcc
	v_xad_u32 v31, v237, -1, v160
	s_waitcnt lgkmcnt(0)
	v_add_f32_e32 v30, v132, v30
	v_cndmask_b32_e64 v30, v208, v30, s[0:1]
	v_cmp_lt_i32_e64 s[0:1], -1, v31
	v_med3_i32 v31, v31, 0, v207
	v_lshl_add_u32 v31, v31, 2, v151
	ds_read_b32 v31, v31 offset:9216
	s_and_b64 s[0:1], s[0:1], vcc
	v_sub_u32_e32 v174, v160, v236
	v_sub_u32_e32 v175, v160, v220
	v_subrev_u32_e32 v177, 17, v179
	s_waitcnt lgkmcnt(0)
	v_add_f32_e32 v31, v133, v31
	v_cndmask_b32_e64 v31, v208, v31, s[0:1]
	v_cmp_lt_i32_e64 s[0:1], -1, v174
	v_med3_i32 v174, v174, 0, v207
	v_lshl_add_u32 v174, v174, 2, v151
	ds_read_b32 v174, v174 offset:9216
	s_and_b64 s[0:1], s[0:1], vcc
	v_max3_f32 v176, v30, s82, v31
	v_subrev_u32_e32 v180, 18, v179
	v_subrev_u32_e32 v181, 19, v179
	s_waitcnt lgkmcnt(0)
	v_add_f32_e32 v174, v134, v174
	v_cndmask_b32_e64 v174, v208, v174, s[0:1]
	v_cmp_lt_i32_e64 s[0:1], -1, v175
	v_med3_i32 v175, v175, 0, v207
	v_lshl_add_u32 v175, v175, 2, v151
	ds_read_b32 v175, v175 offset:9216
	s_and_b64 s[0:1], s[0:1], vcc
	v_subrev_u32_e32 v182, 32, v179
	v_subrev_u32_e32 v183, 33, v179
	v_subrev_u32_e32 v184, 34, v179
	s_waitcnt lgkmcnt(0)
	v_add_f32_e32 v175, v135, v175
	v_cndmask_b32_e64 v175, v208, v175, s[0:1]
	v_max3_f32 v178, v176, v174, v175
	v_add_u32_e32 v176, -16, v179
	v_cmp_lt_i32_e64 s[0:1], -1, v176
	v_med3_i32 v176, v176, 0, v207
	v_lshl_add_u32 v176, v176, 2, v151
	ds_read_b32 v176, v176 offset:9216
	s_and_b64 s[0:1], s[0:1], vcc
	v_subrev_u32_e32 v185, 35, v179
	v_subrev_u32_e32 v186, 48, v179
	v_subrev_u32_e32 v187, 49, v179
	s_waitcnt lgkmcnt(0)
	v_add_f32_e32 v176, v136, v176
	v_cndmask_b32_e64 v176, v208, v176, s[0:1]
	v_cmp_lt_i32_e64 s[0:1], -1, v177
	v_med3_i32 v177, v177, 0, v207
	v_lshl_add_u32 v177, v177, 2, v151
	ds_read_b32 v177, v177 offset:9216
	s_and_b64 s[0:1], s[0:1], vcc
	s_waitcnt lgkmcnt(0)
	v_add_f32_e32 v177, v137, v177
	v_cndmask_b32_e64 v177, v208, v177, s[0:1]
	v_cmp_lt_i32_e64 s[0:1], -1, v180
	v_med3_i32 v180, v180, 0, v207
	v_lshl_add_u32 v180, v180, 2, v151
	ds_read_b32 v180, v180 offset:9216
	s_and_b64 s[0:1], s[0:1], vcc
	v_max3_f32 v178, v178, v176, v177
	s_waitcnt lgkmcnt(0)
	v_add_f32_e32 v180, v138, v180
	v_cndmask_b32_e64 v180, v208, v180, s[0:1]
	v_cmp_lt_i32_e64 s[0:1], -1, v181
	s_and_b64 s[10:11], s[0:1], vcc
	v_med3_i32 v181, v181, 0, v207
	v_cmp_lt_i32_e64 s[0:1], -1, v182
	v_med3_i32 v182, v182, 0, v207
	v_lshl_add_u32 v181, v181, 2, v151
	v_lshl_add_u32 v182, v182, 2, v151
	ds_read_b32 v181, v181 offset:9216
	ds_read_b32 v182, v182 offset:9216
	s_and_b64 s[0:1], s[0:1], vcc
	s_waitcnt lgkmcnt(1)
	v_add_f32_e32 v181, v139, v181
	s_waitcnt lgkmcnt(0)
	v_add_f32_e32 v182, v140, v182
	v_cndmask_b32_e64 v182, v208, v182, s[0:1]
	v_cmp_lt_i32_e64 s[0:1], -1, v183
	v_med3_i32 v183, v183, 0, v207
	v_lshl_add_u32 v183, v183, 2, v151
	ds_read_b32 v183, v183 offset:9216
	s_and_b64 s[0:1], s[0:1], vcc
	v_cndmask_b32_e64 v181, v208, v181, s[10:11]
	v_max3_f32 v178, v178, v180, v181
	s_waitcnt lgkmcnt(0)
	v_add_f32_e32 v183, v141, v183
	v_cndmask_b32_e64 v183, v208, v183, s[0:1]
	v_cmp_lt_i32_e64 s[0:1], -1, v184
	v_med3_i32 v184, v184, 0, v207
	v_lshl_add_u32 v184, v184, 2, v151
	ds_read_b32 v184, v184 offset:9216
	s_and_b64 s[0:1], s[0:1], vcc
	v_max3_f32 v178, v178, v182, v183
	s_waitcnt lgkmcnt(0)
	v_add_f32_e32 v184, v142, v184
	v_cndmask_b32_e64 v184, v208, v184, s[0:1]
	v_cmp_lt_i32_e64 s[0:1], -1, v185
	v_med3_i32 v185, v185, 0, v207
	v_lshl_add_u32 v185, v185, 2, v151
	ds_read_b32 v185, v185 offset:9216
	s_and_b64 s[0:1], s[0:1], vcc
	s_waitcnt lgkmcnt(0)
	v_add_f32_e32 v185, v143, v185
	v_cndmask_b32_e64 v185, v208, v185, s[0:1]
	v_cmp_lt_i32_e64 s[0:1], -1, v186
	v_med3_i32 v186, v186, 0, v207
	v_lshl_add_u32 v186, v186, 2, v151
	ds_read_b32 v186, v186 offset:9216
	s_and_b64 s[0:1], s[0:1], vcc
	v_max3_f32 v178, v178, v184, v185
	s_waitcnt lgkmcnt(0)
	v_add_f32_e32 v186, v144, v186
	v_cndmask_b32_e64 v186, v208, v186, s[0:1]
	v_cmp_lt_i32_e64 s[0:1], -1, v187
	v_med3_i32 v187, v187, 0, v207
	v_lshl_add_u32 v187, v187, 2, v151
	ds_read_b32 v187, v187 offset:9216
	s_and_b64 s[0:1], s[0:1], vcc
	s_waitcnt lgkmcnt(0)
	v_add_f32_e32 v187, v145, v187
	v_cndmask_b32_e64 v187, v208, v187, s[0:1]
	v_max3_f32 v219, v178, v186, v187
	v_subrev_u32_e32 v178, 50, v179
	v_cmp_lt_i32_e64 s[0:1], -1, v178
	v_med3_i32 v178, v178, 0, v207
	v_lshl_add_u32 v178, v178, 2, v151
	ds_read_b32 v178, v178 offset:9216
	s_and_b64 s[0:1], s[0:1], vcc
	v_subrev_u32_e32 v179, 51, v179
	s_waitcnt lgkmcnt(0)
	v_add_f32_e32 v178, v146, v178
	v_cndmask_b32_e64 v178, v208, v178, s[0:1]
	v_cmp_lt_i32_e64 s[0:1], -1, v179
	v_med3_i32 v179, v179, 0, v207
	v_lshl_add_u32 v179, v179, 2, v151
	ds_read_b32 v179, v179 offset:9216
	s_and_b64 vcc, s[0:1], vcc
	s_mov_b64 s[0:1], 0
	s_waitcnt lgkmcnt(0)
	v_add_f32_e32 v179, v147, v179
	v_cndmask_b32_e32 v179, v208, v179, vcc
	v_max3_f32 v219, v219, v178, v179

.LBB0_646:
	v_add_f32_e32 v117, v117, v130
	v_fmac_f32_e32 v117, v216, v116
	v_add_f32_e32 v116, v174, v175
	v_fmac_f32_e32 v116, v29, v30
	s_setprio 1
	v_cvt_pk_bf16_f32 v130, v221, v222
	v_cvt_pk_bf16_f32 v131, v223, v224
	v_cvt_pk_bf16_f32 v132, v225, v227
	v_cvt_pk_bf16_f32 v133, v229, v231
	v_cvt_pk_bf16_f32 v118, v118, v119
	v_cvt_pk_bf16_f32 v119, v120, v121
	v_cvt_pk_bf16_f32 v120, v122, v124
	v_cvt_pk_bf16_f32 v121, v126, v128
	v_add_u32_e32 v29, 0x800, v213
	v_add_u32_e32 v30, 0x1000, v213
	v_add_u32_e32 v138, 0x1800, v213
	v_add_u32_e32 v139, 0x2000, v213
	v_add_u32_e32 v140, 0x2800, v213
	v_add_u32_e32 v141, 0x3000, v213
	v_add_u32_e32 v142, 0x3800, v213
	ds_read2_b64 v[134:137], v138 offset0:96 offset1:100
	s_waitcnt lgkmcnt(3)
	v_mfma_f32_16x16x32_bf16 v[96:99], v[240:243], v[130:133], v[96:99]
	v_mfma_f32_16x16x32_bf16 v[64:67], v[240:243], v[118:121], v[64:67]
	ds_read2_b64 v[240:243], v139 offset0:128 offset1:132
	s_waitcnt lgkmcnt(3)
	v_mfma_f32_16x16x32_bf16 v[92:95], v[248:251], v[130:133], v[92:95]
	v_mfma_f32_16x16x32_bf16 v[60:63], v[248:251], v[118:121], v[60:63]
	ds_read2_b64 v[248:251], v140 offset0:160 offset1:164
	s_waitcnt lgkmcnt(3)
	v_mfma_f32_16x16x32_bf16 v[88:91], v[252:255], v[130:133], v[88:91]
	v_mfma_f32_16x16x32_bf16 v[56:59], v[252:255], v[118:121], v[56:59]
	ds_read2_b64 v[252:255], v141 offset0:192 offset1:196
	s_waitcnt lgkmcnt(3)
	v_mfma_f32_16x16x32_bf16 v[84:87], v[134:137], v[130:133], v[84:87]
	v_mfma_f32_16x16x32_bf16 v[52:55], v[134:137], v[118:121], v[52:55]
	ds_read2_b64 v[134:137], v142 offset0:224 offset1:228
	s_waitcnt lgkmcnt(3)
	v_mfma_f32_16x16x32_bf16 v[80:83], v[240:243], v[130:133], v[80:83]
	v_mfma_f32_16x16x32_bf16 v[48:51], v[240:243], v[118:121], v[48:51]
	ds_read2_b64 v[240:243], v213 offset0:8 offset1:12
	s_waitcnt lgkmcnt(3)
	v_mfma_f32_16x16x32_bf16 v[76:79], v[248:251], v[130:133], v[76:79]
	v_mfma_f32_16x16x32_bf16 v[44:47], v[248:251], v[118:121], v[44:47]
	ds_read2_b64 v[248:251], v29 offset0:40 offset1:44
	s_waitcnt lgkmcnt(3)
	v_mfma_f32_16x16x32_bf16 v[72:75], v[252:255], v[130:133], v[72:75]
	v_mfma_f32_16x16x32_bf16 v[40:43], v[252:255], v[118:121], v[40:43]
	ds_read2_b64 v[252:255], v30 offset0:72 offset1:76
	s_waitcnt lgkmcnt(3)
	v_mfma_f32_16x16x32_bf16 v[36:39], v[134:137], v[118:121], v[36:39]
	v_mfma_f32_16x16x32_bf16 v[68:71], v[134:137], v[130:133], v[68:71]
	ds_read2_b64 v[134:137], v138 offset0:104 offset1:108
	v_cvt_pk_bf16_f32 v118, v226, v228
	v_cvt_pk_bf16_f32 v119, v230, v232
	v_cvt_pk_bf16_f32 v120, v233, v234
	v_cvt_pk_bf16_f32 v121, v235, v31
	v_cvt_pk_bf16_f32 v122, v123, v125
	v_cvt_pk_bf16_f32 v123, v127, v176
	v_cvt_pk_bf16_f32 v124, v187, v218
	v_cvt_pk_bf16_f32 v125, v236, v129
	s_nop 1
	s_waitcnt lgkmcnt(3)
	v_mfma_f32_16x16x32_bf16 v[96:99], v[240:243], v[118:121], v[96:99]
	v_mfma_f32_16x16x32_bf16 v[64:67], v[240:243], v[122:125], v[64:67]
	ds_read2_b64 v[240:243], v139 offset0:136 offset1:140
	s_waitcnt lgkmcnt(3)
	v_mfma_f32_16x16x32_bf16 v[92:95], v[248:251], v[118:121], v[92:95]
	v_mfma_f32_16x16x32_bf16 v[60:63], v[248:251], v[122:125], v[60:63]
	ds_read2_b64 v[248:251], v140 offset0:168 offset1:172
	s_waitcnt lgkmcnt(3)
	v_mfma_f32_16x16x32_bf16 v[88:91], v[252:255], v[118:121], v[88:91]
	v_mfma_f32_16x16x32_bf16 v[56:59], v[252:255], v[122:125], v[56:59]
	ds_read2_b64 v[252:255], v141 offset0:200 offset1:204
	s_waitcnt lgkmcnt(3)
	v_mfma_f32_16x16x32_bf16 v[84:87], v[134:137], v[118:121], v[84:87]
	v_mfma_f32_16x16x32_bf16 v[52:55], v[134:137], v[122:125], v[52:55]
	ds_read2_b64 v[134:137], v142 offset0:232 offset1:236
	s_waitcnt lgkmcnt(3)
	v_mfma_f32_16x16x32_bf16 v[80:83], v[240:243], v[118:121], v[80:83]
	v_mfma_f32_16x16x32_bf16 v[48:51], v[240:243], v[122:125], v[48:51]
	s_waitcnt lgkmcnt(2)
	v_mfma_f32_16x16x32_bf16 v[76:79], v[248:251], v[118:121], v[76:79]
	v_mfma_f32_16x16x32_bf16 v[44:47], v[248:251], v[122:125], v[44:47]
	s_waitcnt lgkmcnt(1)
	v_mfma_f32_16x16x32_bf16 v[72:75], v[252:255], v[118:121], v[72:75]
	v_mfma_f32_16x16x32_bf16 v[40:43], v[252:255], v[122:125], v[40:43]
	s_waitcnt lgkmcnt(0)
	v_mfma_f32_16x16x32_bf16 v[68:71], v[134:137], v[118:121], v[68:71]
	v_mfma_f32_16x16x32_bf16 v[36:39], v[134:137], v[122:125], v[36:39]
	s_setprio 0
	v_mov_b32_e32 v29, v116
	v_mov_b32_e32 v216, v117
	s_andn2_b64 vcc, exec, s[18:19]
	s_cbranch_vccnz .LBB0_648

.LBB0_648:
	s_andn2_b64 vcc, exec, s[16:17]
	s_mov_b64 s[0:1], -1
	s_add_i32 s98, s30, -4
	v_mov_b32_e32 v239, s98
	ds_read_b32 v247, v239 offset:4
	ds_read_b32 v239, v239
	s_waitcnt lgkmcnt(0)
	s_barrier
	s_cbranch_vccnz .LBB0_650
	s_add_i32 s2, s31, 2
	s_mov_b64 s[0:1], 0
.LBB0_650:
	s_andn2_b64 vcc, exec, s[0:1]
	s_cbranch_vccnz .LBB0_622
	ds_read_b128 v[174:177], v214 offset:11328
	ds_read_b128 v[240:243], v214 offset:11392
	ds_read_b128 v[248:251], v214 offset:11456
	ds_read_b128 v[252:255], v214 offset:11520
	s_add_i32 s31, s31, 2
	s_cmp_lt_i32 s31, s28
	s_waitcnt vmcnt(0)
	v_mov_b32_e32 v100, 0
	s_cselect_b64 s[16:17], -1, 0
	v_readfirstlane_b32 s2, v239
	v_readfirstlane_b32 s3, v247
	s_ashr_i32 s98, s2, 5
	v_lshl_add_u32 v239, s98, 2, v195
	ds_read_b32 v247, v239 offset:256
	ds_read_b32 v239, v239
	s_cmp_ge_i32 s31, s28
	v_mov_b32_e32 v101, 0
	v_mov_b32_e32 v102, 0
	v_mov_b32_e32 v103, 0
	v_mov_b32_e32 v104, 0
	v_mov_b32_e32 v105, 0
	v_mov_b32_e32 v106, 0
	v_mov_b32_e32 v107, 0
	v_mov_b32_e32 v108, 0
	v_mov_b32_e32 v109, 0
	v_mov_b32_e32 v110, 0
	v_mov_b32_e32 v111, 0
	v_mov_b32_e32 v112, 0
	v_mov_b32_e32 v113, 0
	v_mov_b32_e32 v114, 0
	v_mov_b32_e32 v115, 0
	s_cbranch_scc1 .LBB0_653
	s_mul_i32 s0, s3, 0x60000
	s_mul_hi_i32 s1, s3, 0x60000
	s_add_u32 s0, s12, s0
	s_addc_u32 s1, s13, s1
	s_lshl_b32 s8, s3, 6
	s_ashr_i32 s9, s8, 31
	v_lshl_add_u64 v[30:31], v[166:167], 1, s[0:1]
	v_lshl_add_u64 v[100:101], v[168:169], 1, s[0:1]
	s_lshl_b64 s[0:1], s[8:9], 1
	s_add_u32 s0, s14, s0
	s_addc_u32 s1, s15, s1
	global_load_dwordx4 v[104:107], v[30:31], off offset:2048
	global_load_dwordx4 v[108:111], v[100:101], off offset:2048
	v_lshl_add_u64 v[30:31], v[170:171], 1, s[0:1]
	v_lshl_add_u64 v[100:101], v[172:173], 1, s[0:1]
	global_load_dwordx4 v[112:115], v[30:31], off
	s_nop 0
	global_load_dwordx4 v[100:103], v[100:101], off
.LBB0_653:
	s_lshl_b32 s0, 1, s2
	s_waitcnt lgkmcnt(0)
	v_and_b32_e32 v31, s0, v247
	v_and_b32_e32 v30, s0, v239
	v_or_b32_e32 v118, v30, v31
	v_cmp_ne_u32_e64 s[8:9], 0, v31
	v_cmp_ne_u32_e64 s[0:1], 0, v30
	v_cmp_ne_u32_e32 vcc, 0, v118
	s_cbranch_vccz .LBB0_678
	s_lshl_b32 s2, s2, 6
	v_cndmask_b32_e64 v30, 0, 1, s[8:9]
	v_cndmask_b32_e64 v31, 0, 1, s[0:1]
	s_sub_i32 s0, s29, s2
	v_lshlrev_b16_e32 v30, 8, v30
	s_cmpk_lt_i32 s0, 0x80
	v_or_b32_e32 v30, v31, v30
	s_cselect_b64 s[18:19], -1, 0
	s_cmpk_gt_i32 s0, 0x7f
	s_setprio 1
	s_waitcnt lgkmcnt(3)
	v_mfma_f32_16x16x32_bf16 v[132:135], v[174:177], v[0:3], 0
	v_mfma_f32_16x16x32_bf16 v[116:119], v[174:177], v[16:19], 0
	ds_read_b128 v[174:177], v214 offset:15680
	s_waitcnt lgkmcnt(3)
	v_mfma_f32_16x16x32_bf16 v[132:135], v[240:243], v[4:7], v[132:135]
	v_mfma_f32_16x16x32_bf16 v[116:119], v[240:243], v[20:23], v[116:119]
	ds_read_b128 v[240:243], v214 offset:15744
	s_waitcnt lgkmcnt(3)
	v_mfma_f32_16x16x32_bf16 v[132:135], v[248:251], v[8:11], v[132:135]
	v_mfma_f32_16x16x32_bf16 v[116:119], v[248:251], v[24:27], v[116:119]
	ds_read_b128 v[248:251], v214 offset:15808
	s_waitcnt lgkmcnt(3)
	v_mfma_f32_16x16x32_bf16 v[132:135], v[252:255], v[12:15], v[132:135]
	v_mfma_f32_16x16x32_bf16 v[116:119], v[252:255], v[32:35], v[116:119]
	ds_read_b128 v[252:255], v214 offset:15872
	s_waitcnt lgkmcnt(3)
	v_mfma_f32_16x16x32_bf16 v[136:139], v[174:177], v[0:3], 0
	v_mfma_f32_16x16x32_bf16 v[120:123], v[174:177], v[16:19], 0
	ds_read_b128 v[174:177], v214 offset:20032
	s_waitcnt lgkmcnt(3)
	v_mfma_f32_16x16x32_bf16 v[136:139], v[240:243], v[4:7], v[136:139]
	v_mfma_f32_16x16x32_bf16 v[120:123], v[240:243], v[20:23], v[120:123]
	ds_read_b128 v[240:243], v214 offset:20096
	s_waitcnt lgkmcnt(3)
	v_mfma_f32_16x16x32_bf16 v[136:139], v[248:251], v[8:11], v[136:139]
	v_mfma_f32_16x16x32_bf16 v[120:123], v[248:251], v[24:27], v[120:123]
	ds_read_b128 v[248:251], v214 offset:20160
	s_waitcnt lgkmcnt(3)
	v_mfma_f32_16x16x32_bf16 v[136:139], v[252:255], v[12:15], v[136:139]
	v_mfma_f32_16x16x32_bf16 v[120:123], v[252:255], v[32:35], v[120:123]
	ds_read_b128 v[252:255], v214 offset:20224
	s_waitcnt lgkmcnt(3)
	v_mfma_f32_16x16x32_bf16 v[140:143], v[174:177], v[0:3], 0
	v_mfma_f32_16x16x32_bf16 v[124:127], v[174:177], v[16:19], 0
	ds_read_b128 v[174:177], v214 offset:24384
	s_waitcnt lgkmcnt(3)
	v_mfma_f32_16x16x32_bf16 v[140:143], v[240:243], v[4:7], v[140:143]
	v_mfma_f32_16x16x32_bf16 v[124:127], v[240:243], v[20:23], v[124:127]
	ds_read_b128 v[240:243], v214 offset:24448
	s_waitcnt lgkmcnt(3)
	v_mfma_f32_16x16x32_bf16 v[140:143], v[248:251], v[8:11], v[140:143]
	v_mfma_f32_16x16x32_bf16 v[124:127], v[248:251], v[24:27], v[124:127]
	ds_read_b128 v[248:251], v214 offset:24512
	s_waitcnt lgkmcnt(3)
	v_mfma_f32_16x16x32_bf16 v[140:143], v[252:255], v[12:15], v[140:143]
	v_mfma_f32_16x16x32_bf16 v[124:127], v[252:255], v[32:35], v[124:127]
	ds_read_b128 v[252:255], v214 offset:24576
	s_waitcnt lgkmcnt(3)
	v_mfma_f32_16x16x32_bf16 v[144:147], v[174:177], v[0:3], 0
	v_mfma_f32_16x16x32_bf16 v[128:131], v[174:177], v[16:19], 0
	s_waitcnt lgkmcnt(2)
	v_mfma_f32_16x16x32_bf16 v[144:147], v[240:243], v[4:7], v[144:147]
	v_mfma_f32_16x16x32_bf16 v[128:131], v[240:243], v[20:23], v[128:131]
	s_waitcnt lgkmcnt(1)
	v_mfma_f32_16x16x32_bf16 v[144:147], v[248:251], v[8:11], v[144:147]
	v_mfma_f32_16x16x32_bf16 v[128:131], v[248:251], v[24:27], v[128:131]
	s_waitcnt lgkmcnt(0)
	v_mfma_f32_16x16x32_bf16 v[144:147], v[252:255], v[12:15], v[144:147]
	v_mfma_f32_16x16x32_bf16 v[128:131], v[252:255], v[32:35], v[128:131]
	s_setprio 0
	v_add_u32_e32 v239, 0x7000, v215
	ds_read2_b64 v[240:243], v239 offset0:8 offset1:12
	v_add_u32_e32 v247, 0x7800, v215
	ds_read2_b64 v[248:251], v247 offset0:40 offset1:44
	v_add_u32_e32 v237, s2, v209
	s_mov_b64 s[0:1], -1
	v_and_b32_e32 v238, 1, v30
	v_or_b32_e32 v236, 2, v237
	v_or_b32_e32 v217, 3, v237
	s_cbranch_scc1 .LBB0_656
	v_sub_u32_e32 v179, v160, v237
	v_med3_i32 v30, v179, 0, v207
	v_lshl_add_u32 v30, v30, 2, v151
	ds_read_b32 v30, v30 offset:9216
	v_cmp_lt_i32_e64 s[0:1], -1, v179
	v_cmp_eq_u32_e32 vcc, 1, v238
	s_and_b64 s[0:1], s[0:1], vcc
	v_xad_u32 v31, v237, -1, v160
	s_waitcnt lgkmcnt(0)
	v_add_f32_e32 v30, v132, v30
	v_cndmask_b32_e64 v30, v208, v30, s[0:1]
	v_cmp_lt_i32_e64 s[0:1], -1, v31
	v_med3_i32 v31, v31, 0, v207
	v_lshl_add_u32 v31, v31, 2, v151
	ds_read_b32 v31, v31 offset:9216
	s_and_b64 s[0:1], s[0:1], vcc
	v_sub_u32_e32 v174, v160, v236
	v_sub_u32_e32 v175, v160, v217
	v_subrev_u32_e32 v177, 17, v179
	s_waitcnt lgkmcnt(0)
	v_add_f32_e32 v31, v133, v31
	v_cndmask_b32_e64 v31, v208, v31, s[0:1]
	v_cmp_lt_i32_e64 s[0:1], -1, v174
	v_med3_i32 v174, v174, 0, v207
	v_lshl_add_u32 v174, v174, 2, v151
	ds_read_b32 v174, v174 offset:9216
	s_and_b64 s[0:1], s[0:1], vcc
	v_max3_f32 v176, v30, s82, v31
	v_subrev_u32_e32 v180, 18, v179
	v_subrev_u32_e32 v181, 19, v179
	s_waitcnt lgkmcnt(0)
	v_add_f32_e32 v174, v134, v174
	v_cndmask_b32_e64 v174, v208, v174, s[0:1]
	v_cmp_lt_i32_e64 s[0:1], -1, v175
	v_med3_i32 v175, v175, 0, v207
	v_lshl_add_u32 v175, v175, 2, v151
	ds_read_b32 v175, v175 offset:9216
	s_and_b64 s[0:1], s[0:1], vcc
	v_subrev_u32_e32 v182, 32, v179
	v_subrev_u32_e32 v183, 33, v179
	v_subrev_u32_e32 v184, 34, v179
	s_waitcnt lgkmcnt(0)
	v_add_f32_e32 v175, v135, v175
	v_cndmask_b32_e64 v175, v208, v175, s[0:1]
	v_max3_f32 v178, v176, v174, v175
	v_add_u32_e32 v176, -16, v179
	v_cmp_lt_i32_e64 s[0:1], -1, v176
	v_med3_i32 v176, v176, 0, v207
	v_lshl_add_u32 v176, v176, 2, v151
	ds_read_b32 v176, v176 offset:9216
	s_and_b64 s[0:1], s[0:1], vcc
	v_subrev_u32_e32 v185, 35, v179
	v_subrev_u32_e32 v186, 48, v179
	v_subrev_u32_e32 v187, 49, v179
	s_waitcnt lgkmcnt(0)
	v_add_f32_e32 v176, v136, v176
	v_cndmask_b32_e64 v176, v208, v176, s[0:1]
	v_cmp_lt_i32_e64 s[0:1], -1, v177
	v_med3_i32 v177, v177, 0, v207
	v_lshl_add_u32 v177, v177, 2, v151
	ds_read_b32 v177, v177 offset:9216
	s_and_b64 s[0:1], s[0:1], vcc
	s_waitcnt lgkmcnt(0)
	v_add_f32_e32 v177, v137, v177
	v_cndmask_b32_e64 v177, v208, v177, s[0:1]
	v_cmp_lt_i32_e64 s[0:1], -1, v180
	v_med3_i32 v180, v180, 0, v207
	v_lshl_add_u32 v180, v180, 2, v151
	ds_read_b32 v180, v180 offset:9216
	s_and_b64 s[0:1], s[0:1], vcc
	v_max3_f32 v178, v178, v176, v177
	s_waitcnt lgkmcnt(0)
	v_add_f32_e32 v180, v138, v180
	v_cndmask_b32_e64 v180, v208, v180, s[0:1]
	v_cmp_lt_i32_e64 s[0:1], -1, v181
	s_and_b64 s[10:11], s[0:1], vcc
	v_med3_i32 v181, v181, 0, v207
	v_cmp_lt_i32_e64 s[0:1], -1, v182
	v_med3_i32 v182, v182, 0, v207
	v_lshl_add_u32 v181, v181, 2, v151
	v_lshl_add_u32 v182, v182, 2, v151
	ds_read_b32 v181, v181 offset:9216
	ds_read_b32 v182, v182 offset:9216
	s_and_b64 s[0:1], s[0:1], vcc
	s_waitcnt lgkmcnt(1)
	v_add_f32_e32 v181, v139, v181
	s_waitcnt lgkmcnt(0)
	v_add_f32_e32 v182, v140, v182
	v_cndmask_b32_e64 v182, v208, v182, s[0:1]
	v_cmp_lt_i32_e64 s[0:1], -1, v183
	v_med3_i32 v183, v183, 0, v207
	v_lshl_add_u32 v183, v183, 2, v151
	ds_read_b32 v183, v183 offset:9216
	s_and_b64 s[0:1], s[0:1], vcc
	v_cndmask_b32_e64 v181, v208, v181, s[10:11]
	v_max3_f32 v178, v178, v180, v181
	s_waitcnt lgkmcnt(0)
	v_add_f32_e32 v183, v141, v183
	v_cndmask_b32_e64 v183, v208, v183, s[0:1]
	v_cmp_lt_i32_e64 s[0:1], -1, v184
	v_med3_i32 v184, v184, 0, v207
	v_lshl_add_u32 v184, v184, 2, v151
	ds_read_b32 v184, v184 offset:9216
	s_and_b64 s[0:1], s[0:1], vcc
	v_max3_f32 v178, v178, v182, v183
	s_waitcnt lgkmcnt(0)
	v_add_f32_e32 v184, v142, v184
	v_cndmask_b32_e64 v184, v208, v184, s[0:1]
	v_cmp_lt_i32_e64 s[0:1], -1, v185
	v_med3_i32 v185, v185, 0, v207
	v_lshl_add_u32 v185, v185, 2, v151
	ds_read_b32 v185, v185 offset:9216
	s_and_b64 s[0:1], s[0:1], vcc
	s_waitcnt lgkmcnt(0)
	v_add_f32_e32 v185, v143, v185
	v_cndmask_b32_e64 v185, v208, v185, s[0:1]
	v_cmp_lt_i32_e64 s[0:1], -1, v186
	v_med3_i32 v186, v186, 0, v207
	v_lshl_add_u32 v186, v186, 2, v151
	ds_read_b32 v186, v186 offset:9216
	s_and_b64 s[0:1], s[0:1], vcc
	v_max3_f32 v178, v178, v184, v185
	s_waitcnt lgkmcnt(0)
	v_add_f32_e32 v186, v144, v186
	v_cndmask_b32_e64 v186, v208, v186, s[0:1]
	v_cmp_lt_i32_e64 s[0:1], -1, v187
	v_med3_i32 v187, v187, 0, v207
	v_lshl_add_u32 v187, v187, 2, v151
	ds_read_b32 v187, v187 offset:9216
	s_and_b64 s[0:1], s[0:1], vcc
	s_waitcnt lgkmcnt(0)
	v_add_f32_e32 v187, v145, v187
	v_cndmask_b32_e64 v187, v208, v187, s[0:1]
	v_max3_f32 v218, v178, v186, v187
	v_subrev_u32_e32 v178, 50, v179
	v_cmp_lt_i32_e64 s[0:1], -1, v178
	v_med3_i32 v178, v178, 0, v207
	v_lshl_add_u32 v178, v178, 2, v151
	ds_read_b32 v178, v178 offset:9216
	s_and_b64 s[0:1], s[0:1], vcc
	v_subrev_u32_e32 v179, 51, v179
	s_waitcnt lgkmcnt(0)
	v_add_f32_e32 v178, v146, v178
	v_cndmask_b32_e64 v178, v208, v178, s[0:1]
	v_cmp_lt_i32_e64 s[0:1], -1, v179
	v_med3_i32 v179, v179, 0, v207
	v_lshl_add_u32 v179, v179, 2, v151
	ds_read_b32 v179, v179 offset:9216
	s_and_b64 vcc, s[0:1], vcc
	s_mov_b64 s[0:1], 0
	s_waitcnt lgkmcnt(0)
	v_add_f32_e32 v179, v147, v179
	v_cndmask_b32_e32 v179, v208, v179, vcc
	v_max3_f32 v218, v218, v178, v179

.LBB0_674:
	v_add_f32_e32 v117, v117, v130
	v_fmac_f32_e32 v117, v216, v116
	v_add_f32_e32 v116, v174, v175
	v_fmac_f32_e32 v116, v29, v30
	s_setprio 1
	v_cvt_pk_bf16_f32 v132, v221, v222
	v_cvt_pk_bf16_f32 v133, v223, v224
	v_cvt_pk_bf16_f32 v134, v225, v227
	v_cvt_pk_bf16_f32 v135, v229, v231
	v_cvt_pk_bf16_f32 v118, v118, v119
	v_cvt_pk_bf16_f32 v119, v120, v121
	v_cvt_pk_bf16_f32 v120, v122, v124
	v_cvt_pk_bf16_f32 v121, v126, v128
	v_add_u32_e32 v29, 0x7000, v215
	v_add_u32_e32 v30, 0x7800, v215
	v_add_u32_e32 v130, 0x8000, v215
	v_add_u32_e32 v140, 0x8800, v215
	v_add_u32_e32 v141, 0x9000, v215
	v_add_u32_e32 v142, 0x9800, v215
	v_add_u32_e32 v143, 0xa000, v215
	v_add_u32_e32 v144, 0xa800, v215
	ds_read2_b64 v[252:255], v130 offset0:72 offset1:76
	ds_read2_b64 v[136:139], v140 offset0:104 offset1:108
	s_waitcnt lgkmcnt(3)
	v_mfma_f32_16x16x32_bf16 v[96:99], v[240:243], v[132:135], v[96:99]
	v_mfma_f32_16x16x32_bf16 v[64:67], v[240:243], v[118:121], v[64:67]
	ds_read2_b64 v[240:243], v141 offset0:136 offset1:140
	s_waitcnt lgkmcnt(3)
	v_mfma_f32_16x16x32_bf16 v[92:95], v[248:251], v[132:135], v[92:95]
	v_mfma_f32_16x16x32_bf16 v[60:63], v[248:251], v[118:121], v[60:63]
	ds_read2_b64 v[248:251], v142 offset0:168 offset1:172
	s_waitcnt lgkmcnt(3)
	v_mfma_f32_16x16x32_bf16 v[88:91], v[252:255], v[132:135], v[88:91]
	v_mfma_f32_16x16x32_bf16 v[56:59], v[252:255], v[118:121], v[56:59]
	ds_read2_b64 v[252:255], v143 offset0:200 offset1:204
	s_waitcnt lgkmcnt(3)
	v_mfma_f32_16x16x32_bf16 v[84:87], v[136:139], v[132:135], v[84:87]
	v_mfma_f32_16x16x32_bf16 v[52:55], v[136:139], v[118:121], v[52:55]
	ds_read2_b64 v[136:139], v144 offset0:232 offset1:236
	s_waitcnt lgkmcnt(3)
	v_mfma_f32_16x16x32_bf16 v[80:83], v[240:243], v[132:135], v[80:83]
	v_mfma_f32_16x16x32_bf16 v[48:51], v[240:243], v[118:121], v[48:51]
	ds_read2_b64 v[240:243], v29 offset0:16 offset1:20
	s_waitcnt lgkmcnt(3)
	v_mfma_f32_16x16x32_bf16 v[76:79], v[248:251], v[132:135], v[76:79]
	v_mfma_f32_16x16x32_bf16 v[44:47], v[248:251], v[118:121], v[44:47]
	ds_read2_b64 v[248:251], v30 offset0:48 offset1:52
	s_waitcnt lgkmcnt(3)
	v_mfma_f32_16x16x32_bf16 v[72:75], v[252:255], v[132:135], v[72:75]
	v_mfma_f32_16x16x32_bf16 v[40:43], v[252:255], v[118:121], v[40:43]
	ds_read2_b64 v[252:255], v130 offset0:80 offset1:84
	s_waitcnt lgkmcnt(3)
	v_mfma_f32_16x16x32_bf16 v[36:39], v[136:139], v[118:121], v[36:39]
	v_mfma_f32_16x16x32_bf16 v[68:71], v[136:139], v[132:135], v[68:71]
	ds_read2_b64 v[136:139], v140 offset0:112 offset1:116
	v_cvt_pk_bf16_f32 v118, v226, v228
	v_cvt_pk_bf16_f32 v119, v230, v232
	v_cvt_pk_bf16_f32 v120, v233, v234
	v_cvt_pk_bf16_f32 v121, v235, v31
	v_cvt_pk_bf16_f32 v122, v123, v125
	v_cvt_pk_bf16_f32 v123, v127, v131
	v_cvt_pk_bf16_f32 v124, v187, v219
	v_cvt_pk_bf16_f32 v125, v236, v129
	s_nop 1
	s_waitcnt lgkmcnt(3)
	v_mfma_f32_16x16x32_bf16 v[96:99], v[240:243], v[118:121], v[96:99]
	v_mfma_f32_16x16x32_bf16 v[64:67], v[240:243], v[122:125], v[64:67]
	ds_read2_b64 v[240:243], v141 offset0:144 offset1:148
	s_waitcnt lgkmcnt(3)
	v_mfma_f32_16x16x32_bf16 v[92:95], v[248:251], v[118:121], v[92:95]
	v_mfma_f32_16x16x32_bf16 v[60:63], v[248:251], v[122:125], v[60:63]
	ds_read2_b64 v[248:251], v142 offset0:176 offset1:180
	s_waitcnt lgkmcnt(3)
	v_mfma_f32_16x16x32_bf16 v[88:91], v[252:255], v[118:121], v[88:91]
	v_mfma_f32_16x16x32_bf16 v[56:59], v[252:255], v[122:125], v[56:59]
	ds_read2_b64 v[252:255], v143 offset0:208 offset1:212
	s_waitcnt lgkmcnt(3)
	v_mfma_f32_16x16x32_bf16 v[84:87], v[136:139], v[118:121], v[84:87]
	v_mfma_f32_16x16x32_bf16 v[52:55], v[136:139], v[122:125], v[52:55]
	ds_read2_b64 v[136:139], v144 offset0:240 offset1:244
	s_waitcnt lgkmcnt(3)
	v_mfma_f32_16x16x32_bf16 v[80:83], v[240:243], v[118:121], v[80:83]
	v_mfma_f32_16x16x32_bf16 v[48:51], v[240:243], v[122:125], v[48:51]
	s_waitcnt lgkmcnt(2)
	v_mfma_f32_16x16x32_bf16 v[76:79], v[248:251], v[118:121], v[76:79]
	v_mfma_f32_16x16x32_bf16 v[44:47], v[248:251], v[122:125], v[44:47]
	s_waitcnt lgkmcnt(1)
	v_mfma_f32_16x16x32_bf16 v[72:75], v[252:255], v[118:121], v[72:75]
	v_mfma_f32_16x16x32_bf16 v[40:43], v[252:255], v[122:125], v[40:43]
	s_waitcnt lgkmcnt(0)
	v_mfma_f32_16x16x32_bf16 v[68:71], v[136:139], v[118:121], v[68:71]
	v_mfma_f32_16x16x32_bf16 v[36:39], v[136:139], v[122:125], v[36:39]
	s_setprio 0
	v_mov_b32_e32 v29, v116
	v_mov_b32_e32 v216, v117
	s_andn2_b64 vcc, exec, s[16:17]
	s_cbranch_vccnz .LBB0_676

.LBB0_676:
	v_mov_b32_e32 v239, s30
	ds_read_b32 v247, v239 offset:4
	ds_read_b32 v239, v239
	s_waitcnt lgkmcnt(0)
	s_barrier
	s_add_i32 s30, s30, 8
	s_cmp_lt_i32 s31, s28
	s_cbranch_scc1 .LBB0_623
	s_branch .LBB0_681
